# P3: five workgroup classes run attention after 0..4 of their conv units (finer VALU/MFMA mixing across CUs than the odd/even split)
# speedup vs baseline: 1.0016x; 1.0016x over previous
; #define LAS __attribute__((address_space(3)))
; DI bf16 f2bf(float f) { return (bf16)(pk2(f, 0.f) & 0xffffu); }
; template <int L, int NB>
; DI void conv_unit(const Frame& F, int c, const bf16* FRg, const float* F0, const float* hyD, const bf16* UT, bf16* YT, int tok0, bool dry) {
;     constexpr int RS = L / 32, LOGRS = (RS == 512 ? 9 : 7), JB = 32 / NB, WN = (NB == 1 ? 2560 : 640), WCH = WN / 8, WSTEPS = (NB == 1 ? 120 : 24), BST = (NB == 1 ? 5120 : 1408)  ;
;     constexpr int NSTEPS = (L + RS) / 16, NWIN = (NSTEPS + WSTEPS - 1) / WSTEPS;
;     static_assert(NB * WCH == 320 && WSTEPS % 6 == 0 && (NSTEPS % WSTEPS) % 6 == 0, "window chunks / steps");
;     LAS unsigned char* fr = F.lds; LAS unsigned char* uw = F.lds + CONV_FR_MAX + F.wave * 5632;
;     const int lane = F.lane, wave = F.wave, r32 = lane & 31, hh = lane >> 5;
;     const bf16* ubase = UT + (size_t)c * MTOK;
;     const u32x4 z4 = {0u, 0u, 0u, 0u};
;     u32x4 lo[5], hi[5];
;     ...
;     CONV_ISSUE(0);
;     {
;         const bf16* frow = FRg + (size_t)c * 2 * L;
;         for (int ch = F.tid; ch < 2 * L / 8; ch += 512) { const u32x4 v = *(const u32x4*)(frow + 8 * ch); const int x0 = 8 * ch; *(LAS u32x4*)(fr + 2 * x0 + ((x0 >> LOGRS) << 4)) = v; }
;         __syncthreads();
;         if (F.tid == 0) *(LAS bf16*)(fr + 2 * L + ((L >> LOGRS) << 4)) = f2bf(F0[c] + F0[512 + c] + hyD[c]);
;         __syncthreads();
;     }
;     f32x16 acc0, acc1;
; #pragma unroll
;     for (int i = 0; i < 16; ++i) { acc0[i] = 0.f; acc1[i] = 0.f; }
;     const int jj = r32 % JB, bb = r32 / JB;
;     const int xA0 = L - RS * r32 + 8 * hh - RS;
;     const LAS unsigned char* ubp0 = uw + bb * BST + hh * WN + 16 * jj;
;     const LAS unsigned char* ubp1 = uw + bb * BST + (1 - hh) * WN + 16 * (jj + hh);
; __global__ void __launch_bounds__(512, 2) hybrid_fwd(Args args) {
;     ...
;         if (sub & 1) for (int cu = F.bid; cu < 1024; cu += F.G) {
;             if (cu < 512) conv_unit<16384, 1>(F, cu, FRS, F0 + 1024, args.in[15], UT, UT, TOKP, dry);
;             else conv_unit<4096, 4>(F, cu - 512, FRP, F0, args.in[15], UT, UT, 0, dry);
;         }
.LBB0_753:
	v_mov_b32_e32 v255, 0
	v_mov_b32_e32 v247, 1
	s_cmp_lt_i32 s84, 4
	s_cselect_b64 s[2:3], -1, 0
	s_and_b64 s[0:1], s[2:3], s[0:1]
	v_writelane_b32 v246, s0, 34
	s_andn2_b64 vcc, exec, s[0:1]
	s_nop 0
	v_writelane_b32 v246, s1, 35
	s_cbranch_vccnz .LBB0_1110
	v_writelane_b32 v246, s96, 30
	s_cmpk_gt_i32 s33, 0x3ff
	s_nop 0
	v_writelane_b32 v246, s97, 31
	v_writelane_b32 v246, s87, 36
	v_writelane_b32 v246, s94, 37
	s_nop 1
	v_writelane_b32 v246, s95, 38
	v_writelane_b32 v246, s84, 39
	s_nop 1
	v_writelane_b32 v246, s85, 40
	s_cbranch_scc1 .LBB0_1054
	v_mov_b32_e32 v247, 0
	v_mov_b32_e32 v255, s33
	s_lshr_b32 s0, s33, 3
	s_mul_i32 s0, s0, 5
	s_lshr_b32 s0, s0, 5
	s_lshl_b32 s1, s0, 8
	s_add_i32 s1, s1, s33
	v_mov_b32_e32 v254, s1
	s_cmp_eq_u32 s0, 0
	s_cbranch_scc1 .LBB0_1054
.Lp3_conv_start:
	v_or_b32_e32 v0, 64, v148
	s_mov_b32 s1, 0x3333334
	v_or_b32_e32 v4, 0x80, v148
	v_or_b32_e32 v10, 0xc0, v148
	v_mul_hi_u32 v2, v0, s1
	v_mul_hi_u32 v6, v4, s1
	v_mul_hi_u32 v12, v10, s1
	v_mul_u32_u24_e32 v5, 0x50, v2
	v_mul_u32_u24_e32 v9, 0x50, v6
	v_mul_u32_u24_e32 v13, 0x50, v12
	v_readlane_b32 s22, v246, 29
	v_sub_u32_e32 v0, v0, v5
	v_sub_u32_e32 v4, v4, v9
	v_sub_u32_e32 v10, v10, v13
	s_mul_i32 s26, s22, 0x1600
	s_movk_i32 s0, 0xff80
	v_lshlrev_b32_e32 v3, 3, v0
	v_lshlrev_b32_e32 v7, 12, v2
	v_lshlrev_b32_e32 v8, 3, v4
	v_lshlrev_b32_e32 v11, 12, v6
	v_lshlrev_b32_e32 v14, 3, v10
	v_lshlrev_b32_e32 v15, 12, v12
	v_add3_u32 v153, v3, v7, s0
	v_add3_u32 v156, v8, v11, s0
	v_add3_u32 v157, v14, v15, s0
	s_add_i32 s0, s26, 0
	s_add_i32 s24, s0, 0x10400
	v_lshrrev_b32_e32 v19, 5, v148
	v_bfe_u32 v21, v150, 3, 2
	s_movk_i32 s0, 0x580
	v_mov_b32_e32 v23, s24
	v_mad_u32_u24 v24, v21, s0, v23
	s_movk_i32 s0, 0x280
	v_xor_b32_e32 v27, 1, v19
	v_mad_u32_u24 v25, v19, s0, v24
	v_mad_u32_u24 v24, v27, s0, v24
	v_readlane_b32 s0, v246, 18
	s_cmpk_gt_u32 s0, 0x7f
	v_cmp_lt_u32_e64 s[6:7], 15, v0
	v_cmp_lt_u32_e64 s[8:9], 14, v0
	v_or_b32_e32 v16, 0x100, v148
	s_cselect_b64 s[42:43], -1, 0
	s_bitcmp1_b32 s0, 6
	v_and_b32_e32 v0, 1, v0
	v_mul_hi_u32 v17, v16, s1
	s_cselect_b64 s[44:45], -1, 0
	s_lshr_b32 s70, s0, 7
	v_mov_b32_e32 v32, 0x280
	v_cmp_eq_u32_e64 s[0:1], 1, v0
	v_mul_u32_u24_e32 v2, 0x580, v2
	v_mul_u32_u24_e32 v18, 0x50, v17
	v_cndmask_b32_e64 v0, 0, v32, s[0:1]
	v_add3_u32 v33, s24, v2, v0
	v_and_b32_e32 v2, 1, v4
	v_cmp_eq_u32_e64 s[0:1], 1, v2
	v_mul_u32_u24_e32 v0, 0x580, v6
	v_sub_u32_e32 v16, v16, v18
	v_cndmask_b32_e64 v2, 0, v32, s[0:1]
	v_add3_u32 v35, s24, v0, v2
	v_and_b32_e32 v2, 1, v10
	v_cmp_eq_u32_e64 s[0:1], 1, v2
	v_mul_u32_u24_e32 v0, 0x580, v12
	v_and_b32_e32 v1, 31, v150
	v_cndmask_b32_e64 v2, 0, v32, s[0:1]
	v_add3_u32 v37, s24, v0, v2
	v_and_b32_e32 v0, 1, v16
	v_lshlrev_b32_e32 v22, 3, v19
	v_lshlrev_b32_e32 v29, 7, v1
	v_and_b32_e32 v31, 1, v150
	v_cmp_eq_u32_e64 s[0:1], 1, v0
	v_sub_u32_e32 v29, v22, v29
	v_cmp_eq_u32_e32 vcc, 1, v31
	v_cndmask_b32_e64 v0, 0, v32, s[0:1]
	v_and_b32_e32 v34, 0x3f0, v3
	v_cndmask_b32_e32 v31, 0, v32, vcc
	v_add_u32_e32 v32, s24, v0
	v_add_u32_e32 v0, 0x1e80, v29
	v_lshl_add_u32 v39, v0, 1, 0
	v_lshrrev_b32_e32 v0, 3, v0
	v_and_b32_e32 v40, 0x1ffffff0, v0
	v_add_u32_e32 v0, 0x1ea0, v29
	v_lshl_add_u32 v41, v0, 1, 0
	v_lshrrev_b32_e32 v0, 3, v0
	v_and_b32_e32 v42, 0x1ffffff0, v0
	v_add_u32_e32 v0, 0x1ec0, v29
	v_lshl_add_u32 v43, v0, 1, 0
	v_lshrrev_b32_e32 v0, 3, v0
	v_and_b32_e32 v44, 0x1ffffff0, v0
	v_add_u32_e32 v0, 0x1ee0, v29
	v_lshl_add_u32 v45, v0, 1, 0
	v_lshrrev_b32_e32 v0, 3, v0
	v_and_b32_e32 v46, 0x1ffffff0, v0
	v_add_u32_e32 v0, 0x1f00, v29
	v_lshl_add_u32 v47, v0, 1, 0
	v_lshrrev_b32_e32 v0, 3, v0
	v_and_b32_e32 v48, 0x1ffffff0, v0
	v_add_u32_e32 v0, 0x1f20, v29
	v_lshl_add_u32 v49, v0, 1, 0
	v_lshrrev_b32_e32 v0, 3, v0
	v_and_b32_e32 v50, 0x1ffffff0, v0
	v_add_u32_e32 v0, 0x1f40, v29
	v_lshl_add_u32 v51, v0, 1, 0
	v_lshrrev_b32_e32 v0, 3, v0
	v_and_b32_e32 v52, 0x1ffffff0, v0
	v_add_u32_e32 v0, 0x1f60, v29
	v_lshl_add_u32 v53, v0, 1, 0
	v_lshrrev_b32_e32 v0, 3, v0
	v_and_b32_e32 v54, 0x1ffffff0, v0
	v_add_u32_e32 v0, 0x1f80, v29
	v_lshl_add_u32 v55, v0, 1, 0
	v_lshrrev_b32_e32 v0, 3, v0
	v_and_b32_e32 v56, 0x1ffffff0, v0
	v_add_u32_e32 v0, 0x1fa0, v29
	v_lshl_add_u32 v57, v0, 1, 0
	v_lshrrev_b32_e32 v0, 3, v0
	v_and_b32_e32 v58, 0x1ffffff0, v0
	v_add_u32_e32 v0, 0x1fc0, v29
	v_lshl_add_u32 v59, v0, 1, 0
	v_lshrrev_b32_e32 v0, 3, v0
	v_and_b32_e32 v60, 0x1ffffff0, v0
	v_add_u32_e32 v0, 0x1fe0, v29
	v_lshl_add_u32 v61, v0, 1, 0
	v_lshrrev_b32_e32 v0, 3, v0
	v_lshrrev_b32_e32 v3, 2, v150
	v_and_b32_e32 v20, 7, v150
	v_and_b32_e32 v62, 0x1ffffff0, v0
	v_lshlrev_b32_e32 v0, 13, v21
	v_lshlrev_b32_e32 v2, 10, v19
	v_and_b32_e32 v68, 0xf0, v3
	v_add_u32_e32 v3, 0x200, v150
	v_cmp_lt_u32_e64 s[10:11], 15, v4
	v_cmp_lt_u32_e64 s[12:13], 14, v4
	v_add3_u32 v0, 0, v0, v2
	v_lshlrev_b32_e32 v2, 5, v20
	s_lshl_b32 s0, s22, 1
	v_lshlrev_b32_e32 v4, 3, v3
	v_lshl_add_u32 v69, v3, 4, 0
	v_lshrrev_b32_e32 v3, 2, v3
	v_add3_u32 v160, v0, v2, s0
	v_mov_b32_e32 v0, 0xa00
	v_and_b32_e32 v70, 0x1f0, v3
	v_or_b32_e32 v3, 0x400, v150
	v_cndmask_b32_e32 v0, 0, v0, vcc
	v_lshlrev_b32_e32 v6, 3, v3
	v_lshl_add_u32 v71, v3, 4, 0
	v_lshrrev_b32_e32 v3, 2, v3
	v_lshlrev_b32_e32 v149, 3, v148
	s_movk_i32 s25, 0x3f0
	v_add_u32_e32 v165, s24, v0
	v_mov_b32_e32 v0, 0x200
	v_and_b32_e32 v72, 0x1f0, v3
	v_add_u32_e32 v3, 0x600, v150
	v_and_b32_e32 v36, 0x3f0, v8
	v_bitop3_b32 v64, v149, s25, v0 bitop3:0xc8
	s_movk_i32 s1, 0x5f0
	v_mov_b32_e32 v0, 0x400
	v_lshlrev_b32_e32 v8, 3, v3
	v_lshl_add_u32 v73, v3, 4, 0
	v_lshrrev_b32_e32 v3, 2, v3
	v_bitop3_b32 v65, v149, s1, v0 bitop3:0xc8
	s_movk_i32 s1, 0x7f0
; #define LAS __attribute__((address_space(3)))
; DI bf16 f2bf(float f) { return (bf16)(pk2(f, 0.f) & 0xffffu); }
; template <int L, int NB>
; DI void conv_unit(const Frame& F, int c, const bf16* FRg, const float* F0, const float* hyD, const bf16* UT, bf16* YT, int tok0, bool dry) {
;     ...
;     LAS unsigned char* fr = F.lds; LAS unsigned char* uw = F.lds + CONV_FR_MAX + F.wave * 5632;
;     const int lane = F.lane, wave = F.wave, r32 = lane & 31, hh = lane >> 5;
;     const bf16* ubase = UT + (size_t)c * MTOK;
;     const u32x4 z4 = {0u, 0u, 0u, 0u};
;     u32x4 lo[5], hi[5];
;     ...
;     CONV_ISSUE(0);
;     {
;         const bf16* frow = FRg + (size_t)c * 2 * L;
;         for (int ch = F.tid; ch < 2 * L / 8; ch += 512) { const u32x4 v = *(const u32x4*)(frow + 8 * ch); const int x0 = 8 * ch; *(LAS u32x4*)(fr + 2 * x0 + ((x0 >> LOGRS) << 4)) = v; }
;         __syncthreads();
;         if (F.tid == 0) *(LAS bf16*)(fr + 2 * L + ((L >> LOGRS) << 4)) = f2bf(F0[c] + F0[512 + c] + hyD[c]);
;         __syncthreads();
;     }
;     f32x16 acc0, acc1;
; #pragma unroll
;     for (int i = 0; i < 16; ++i) { acc0[i] = 0.f; acc1[i] = 0.f; }
;     const int jj = r32 % JB, bb = r32 / JB;
;     const int xA0 = L - RS * r32 + 8 * hh - RS;
;     const LAS unsigned char* ubp0 = uw + bb * BST + hh * WN + 16 * jj;
;     const LAS unsigned char* ubp1 = uw + bb * BST + (1 - hh) * WN + 16 * (jj + hh);
	v_mov_b32_e32 v0, 0x600
	v_and_b32_e32 v74, 0x3f0, v3
	v_or_b32_e32 v3, 0x800, v150
	v_cmp_lt_u32_e64 s[14:15], 15, v10
	v_cmp_lt_u32_e64 s[16:17], 14, v10
	v_bitop3_b32 v66, v149, s1, v0 bitop3:0xc8
	s_movk_i32 s1, 0x9f0
	v_mov_b32_e32 v0, 0x800
	v_lshlrev_b32_e32 v10, 3, v3
	v_lshl_add_u32 v75, v3, 4, 0
	v_lshrrev_b32_e32 v3, 2, v3
	v_bitop3_b32 v67, v149, s1, v0 bitop3:0xc8
	v_lshlrev_b32_e32 v0, 9, v1
	v_and_b32_e32 v76, 0x2f0, v3
	v_add_u32_e32 v3, 0xa00, v150
	v_sub_u32_e32 v22, v22, v0
	v_lshl_add_u32 v0, v19, 12, 0
	v_lshlrev_b32_e32 v2, 5, v1
	v_lshlrev_b32_e32 v12, 3, v3
	v_lshl_add_u32 v77, v3, 4, 0
	v_lshrrev_b32_e32 v3, 2, v3
	v_add3_u32 v167, v0, v2, s0
	v_and_b32_e32 v78, 0x3f0, v3
	v_or_b32_e32 v3, 0xc00, v150
	s_movk_i32 s0, 0xe00
	v_lshlrev_b32_e32 v18, 3, v16
	v_cmp_lt_u32_e64 s[18:19], 15, v16
	v_cmp_lt_u32_e64 s[20:21], 14, v16
	v_add_u32_e32 v31, s24, v31
	v_and_b32_e32 v38, 0x3f0, v14
	v_lshlrev_b32_e32 v14, 3, v3
	v_lshl_add_u32 v79, v3, 4, 0
	v_lshrrev_b32_e32 v16, 2, v3
	v_cmp_gt_u32_e64 s[24:25], s0, v3
	v_add_u32_e32 v3, 0xe00, v150
	v_and_b32_e32 v80, 0x3f0, v16
	v_lshlrev_b32_e32 v16, 3, v3
	v_lshl_add_u32 v81, v3, 4, 0
	v_lshrrev_b32_e32 v3, 2, v3
	v_mov_b32_e32 v0, 0
	v_lshlrev_b32_e32 v2, 4, v150
	v_and_b32_e32 v82, 0x7f0, v3
	v_and_b32_e32 v3, 0x3f0, v150
	v_add3_u32 v170, v2, v3, 0
	v_mov_b32_e32 v3, v0
	v_add_u32_e32 v30, 0xf80, v29
	v_add_u32_e32 v168, 0, v2
	v_lshl_add_u64 v[2:3], s[82:83], 0, v[2:3]
	s_mov_b64 s[0:1], 0xc000000
	v_lshl_add_u64 v[154:155], v[2:3], 0, s[0:1]
	v_lshrrev_b32_e32 v2, 3, v30
	v_and_b32_e32 v171, 0x1ffffff0, v2
	v_lshlrev_b32_e32 v2, 4, v19
	v_add_u32_e32 v3, v171, v2
	v_lshlrev_b32_e32 v30, 8, v1
	v_sub_u32_e32 v3, v3, v30
	v_add_u32_e32 v172, 0x1f00, v3
	v_add_u32_e32 v3, 0x10e0, v29
	v_lshrrev_b32_e32 v3, 3, v3
	v_and_b32_e32 v3, 0x3f0, v3
	v_add_u32_e32 v3, v3, v2
	v_sub_u32_e32 v3, v3, v30
	v_add_u32_e32 v173, 0x21c0, v3
	v_add_u32_e32 v3, 0x10c0, v29
	v_lshrrev_b32_e32 v3, 3, v3
	v_and_b32_e32 v3, 0x3f0, v3
	v_add_u32_e32 v3, v3, v2
	v_sub_u32_e32 v3, v3, v30
	v_add_u32_e32 v175, 0x2180, v3
	v_add_u32_e32 v3, 0x10a0, v29
	v_lshrrev_b32_e32 v3, 3, v3
	v_and_b32_e32 v3, 0x3f0, v3
	v_add_u32_e32 v3, v3, v2
	v_sub_u32_e32 v3, v3, v30
	v_add_u32_e32 v176, 0x2140, v3
	v_add_u32_e32 v3, 0x1080, v29
	v_lshrrev_b32_e32 v3, 3, v3
	v_and_b32_e32 v3, 0x3f0, v3
	v_add_u32_e32 v3, v3, v2
	v_sub_u32_e32 v3, v3, v30
	v_add_u32_e32 v177, 0x2100, v3
	v_add_u32_e32 v3, 0x1060, v29
	v_lshrrev_b32_e32 v3, 3, v3
	v_and_b32_e32 v3, 0x3f0, v3
	v_add_u32_e32 v3, v3, v2
	v_sub_u32_e32 v3, v3, v30
	v_add_u32_e32 v178, 0x20c0, v3
	v_add_u32_e32 v3, 0x1040, v29
	v_lshrrev_b32_e32 v3, 3, v3
	v_and_b32_e32 v3, 0x3f0, v3
	v_add_u32_e32 v3, v3, v2
	v_sub_u32_e32 v3, v3, v30
	v_add_u32_e32 v179, 0x2080, v3
	v_add_u32_e32 v3, 0x1020, v29
	v_lshrrev_b32_e32 v3, 3, v3
	v_and_b32_e32 v3, 0x3f0, v3
	v_add_u32_e32 v3, v3, v2
	v_sub_u32_e32 v3, v3, v30
	v_add_u32_e32 v180, 0x2040, v3
	v_add_u32_e32 v3, 0x1000, v29
	v_lshrrev_b32_e32 v3, 3, v3
	v_and_b32_e32 v3, 0x3f0, v3
	s_add_u32 s94, s82, 0x61000
	v_add_u32_e32 v3, v3, v2
	s_addc_u32 s95, s83, 0
	v_sub_u32_e32 v3, v3, v30
	s_lshl_b32 s1, s33, 7
	v_add_u32_e32 v181, 0x2000, v3
	v_mul_u32_u24_e32 v3, 0x280, v17
	v_add_u32_e32 v183, s1, v149
	s_movk_i32 s27, 0xa00
	v_sub_u32_e32 v182, v149, v3
	v_sub_u32_e32 v184, v183, v3
	v_lshlrev_b32_e32 v3, 3, v13
	v_add_u32_e32 v13, v183, v15
	v_lshlrev_b32_e32 v26, 4, v20
	v_add_lshl_u32 v28, v19, v20, 4
	v_mad_u32_u24 v20, v19, s27, v23
	v_lshlrev_b32_e32 v21, 4, v1
	v_mul_u32_u24_e32 v63, 0xa00, v27
	v_mad_u32_u24 v23, v27, s27, v23
	v_add_lshl_u32 v27, v19, v1, 4
	v_sub_u32_e32 v185, v149, v3
	v_sub_u32_e32 v186, v13, v3
	v_lshlrev_b32_e32 v3, 3, v9
	v_add_u32_e32 v9, v183, v11
	v_lshlrev_b32_e32 v1, 10, v1
	v_sub_u32_e32 v187, v149, v3
	v_sub_u32_e32 v188, v9, v3
	v_lshlrev_b32_e32 v3, 3, v5
	v_add_u32_e32 v5, v183, v7
	v_sub_u32_e32 v192, v2, v1
	v_mov_b32_e32 v1, s26
	v_add_u32_e32 v158, 0x2f80, v18
	v_and_b32_e32 v159, 0x1f0, v149
	v_and_b32_e32 v18, 0x3f0, v18
	v_sub_u32_e32 v189, v149, v3
	v_sub_u32_e32 v190, v5, v3
	v_add_u32_e32 v3, s1, v152
	v_mad_u32_u24 v1, v19, s27, v1
	v_add_u32_e32 v151, 0xffffff80, v149
	v_cmp_lt_u32_e64 s[2:3], 15, v148
	v_cmp_lt_u32_e64 s[4:5], 14, v148
	s_mov_b32 s36, 0
	v_cmp_eq_u32_e64 s[22:23], 63, v148
	v_or_b32_e32 v161, 0x200, v149
	v_or_b32_e32 v162, 0x400, v149
	v_or_b32_e32 v163, 0x600, v149
	v_or_b32_e32 v164, 0x800, v149
	v_add_u32_e32 v166, 0x3e00, v22
	v_add_u32_e32 v169, 0xfffffe00, v150
	s_add_i32 s0, s33, 0xfffffe00
	v_sub_u32_e32 v174, v2, v30
	s_movk_i32 s87, 0x1000
	s_lshl_b32 s71, s89, 7
	v_add_u32_e32 v191, 0xffff0000, v3
	v_add_u32_e32 v193, 0x3e80, v22
	v_add3_u32 v194, v63, s26, v27
	v_or_b32_e32 v195, v1, v21
	s_mov_b32 s97, 0x1000706
	s_movk_i32 s84, 0xff8
	v_add_u32_e32 v196, v39, v40
	v_add_u32_e32 v197, v41, v42
	v_add_u32_e32 v198, v43, v44
	v_add_u32_e32 v199, v45, v46
	v_add_u32_e32 v200, v47, v48
	v_add_u32_e32 v201, v49, v50
	v_add_u32_e32 v202, v51, v52
	v_add_u32_e32 v203, v53, v54
	v_add_u32_e32 v204, v55, v56
	v_add_u32_e32 v205, v57, v58
	v_add_u32_e32 v206, v59, v60
	v_add_u32_e32 v207, v61, v62
	s_movk_i32 s85, 0x5ff
	s_movk_i32 s50, 0x4000
	v_lshlrev_b32_e32 v208, 1, v152
	v_add_u32_e32 v209, v168, v68
	v_lshlrev_b32_e32 v210, 1, v4
	v_add_u32_e32 v211, v69, v70
	v_lshlrev_b32_e32 v212, 1, v6
	v_add_u32_e32 v213, v71, v72
	v_lshlrev_b32_e32 v214, 1, v8
	v_add_u32_e32 v215, v73, v74
	v_lshlrev_b32_e32 v216, 1, v10
	v_add_u32_e32 v217, v75, v76
	v_lshlrev_b32_e32 v218, 1, v12
	v_add_u32_e32 v219, v77, v78
	v_lshlrev_b32_e32 v220, 1, v14
	v_add_u32_e32 v221, v79, v80
	v_lshlrev_b32_e32 v222, 1, v16
	v_add_u32_e32 v223, v81, v82
	v_add_u32_e32 v224, v165, v64
	v_add_u32_e32 v225, v165, v65
	v_add_u32_e32 v226, v165, v66
	v_add_u32_e32 v227, v165, v67
	s_movk_i32 s51, 0x3ff8
	v_add_u32_e32 v228, v20, v21
	v_add_u32_e32 v229, v23, v27
	v_add_u32_e32 v230, v31, v159
	v_add_u32_e32 v231, v33, v34
	v_add_u32_e32 v232, v35, v36
	v_add_u32_e32 v233, v37, v38
	v_add_u32_e32 v234, v32, v18
	v_add_u32_e32 v235, v25, v26
	v_add_u32_e32 v236, v24, v28
	s_mov_b32 s78, s33
	v_readfirstlane_b32 s98, v255
; __global__ void __launch_bounds__(512, 2) hybrid_fwd(Args args) {
;     ...
;         if (sub & 1) for (int cu = F.bid; cu < 1024; cu += F.G) {
;             if (cu < 512) conv_unit<16384, 1>(F, cu, FRS, F0 + 1024, args.in[15], UT, UT, TOKP, dry);
;             else conv_unit<4096, 4>(F, cu - 512, FRP, F0, args.in[15], UT, UT, 0, dry);
;         }
.Lp3_skip_units:
	s_cmp_eq_u32 s78, s98
	s_cbranch_scc1 .LBB0_757
	s_add_i32 s78, s78, s89
	s_add_i32 s0, s0, s89
	v_add_u32_e32 v184, s71, v184
	v_add_u32_e32 v186, s71, v186
	v_add_u32_e32 v188, s71, v188
	v_add_u32_e32 v190, s71, v190
	v_add_u32_e32 v183, s71, v183
	v_add_u32_e32 v191, s71, v191
	s_branch .Lp3_skip_units
	s_nop 0
	s_nop 0
	s_nop 0
	s_nop 0
	s_nop 0
	s_nop 0
	s_nop 0
	s_nop 0
.LBB0_756:
	s_add_i32 s78, s78, s89
	s_add_i32 s0, s0, s89
	v_add_u32_e32 v184, s71, v184
	v_add_u32_e32 v186, s71, v186
	v_add_u32_e32 v188, s71, v188
	v_add_u32_e32 v190, s71, v190
	v_add_u32_e32 v183, s71, v183
	v_cmp_eq_u32_e32 vcc, s78, v254
	s_cbranch_vccz .Lp3_noatt
	v_cmp_eq_u32_e32 vcc, 0, v247
	s_cbranch_vccz .Lp3_noatt
	v_mov_b32_e32 v255, s78
	s_branch .LBB0_1054
.Lp3_noatt:
	s_cmpk_gt_i32 s78, 0x3ff
	v_add_u32_e32 v191, s71, v191
	s_cbranch_scc1 .LBB0_1054

; #define LAS __attribute__((address_space(3)))
; __device__ __forceinline__ unsigned xb_add(unsigned* p, unsigned v) { return __hip_atomic_fetch_add(p, v, __ATOMIC_RELAXED, __HIP_MEMORY_SCOPE_AGENT); }
; __device__ __forceinline__ void xcd_barrier(const XcdBarrier& b) {
;     asm volatile("s_waitcnt vmcnt(0)" ::: "memory");
;     __syncthreads();
;     if (threadIdx.x == 0) {
;         unsigned* bar = b.bar;
;         __builtin_amdgcn_s_waitcnt(0);
;         unsigned nloc = b.st[0], nx = b.st[1];
;         if (nloc == 0u) { xcd_barrier_complete(bar, b.x, nloc, nx); b.st[0] = nloc; b.st[1] = nx; }
;         const unsigned old = xb_add(&bar[XB_XSUB(b.x)], 1u);
; __global__ void __launch_bounds__(512, 2) hybrid_fwd(Args args) {
;     ...
;         if (sub & 1) for (int cu = F.bid; cu < 1024; cu += F.G) {
;             if (cu < 512) conv_unit<16384, 1>(F, cu, FRS, F0 + 1024, args.in[15], UT, UT, TOKP, dry);
;             else conv_unit<4096, 4>(F, cu - 512, FRP, F0, args.in[15], UT, UT, 0, dry);
;         }
;         __syncthreads();
;         int cur_head = -1; LAS float* tab = (LAS float*)(F.lds + F.wave * 2560); LAS unsigned char* wl = F.lds + 20480 + F.wave * ATT_WAVE_LDS;
;         if (sub & 2) {
;             if ((F.G & 7) == 0) {
;                 const int h = F.bid & 7, NWV = (F.G >> 3) * 8;
;                 for (int e = (F.bid >> 3) * 8 + F.wave; e < 1024; e += NWV)
;                     attn_unit(e >> 1, h, e & 1, Qb, Kb, VT, Qb, args.in[4], tab, wl, F.lane, cur_head, dry);
;             } else {
;                 for (int u = gw; u < 8192; u += NGW) attn_unit(u >> 4, (u >> 1) & 7, u & 1, Qb, Kb, VT, Qb, args.in[4], tab, wl, F.lane, cur_head, dry);
;             }
;         }
;     }
;     DUP_END(3)
;     SEAM(3);
.LBB0_1110:
	v_cmp_ne_u32_e32 vcc, 0, v247
	s_cbranch_vccnz .Lp3_done
	v_mov_b32_e32 v247, 1
	v_readfirstlane_b32 s0, v255
	s_cmpk_gt_i32 s0, 0x3ff
	s_cbranch_scc1 .Lp3_done
	s_sub_u32 s0, s96, 0xd8
	s_subb_u32 s1, s97, 0
	s_load_dwordx2 s[30:31], s[0:1], 0x78
	s_add_u32 s34, s82, 0x60000
	s_addc_u32 s35, s83, 0
	s_add_u32 s40, s82, 0xc800000
	s_addc_u32 s41, s83, 0
	s_waitcnt vmcnt(0) lgkmcnt(0)
	s_barrier
	s_branch .Lp3_conv_start
.Lp3_done:
	v_mov_b32_e32 v255, 0
	s_nop 0
	s_nop 0
	s_nop 0
	s_nop 0
	s_nop 0
	s_nop 0
	s_nop 0
	s_nop 0
	s_nop 0
	s_nop 0
	s_nop 0
	s_nop 0
	s_nop 0
	s_nop 0
	s_cmp_gt_i32 s85, 4
	v_readlane_b32 s2, v246, 34
	s_cselect_b64 s[0:1], -1, 0
	v_readlane_b32 s3, v246, 35
	s_and_b64 s[2:3], s[2:3], s[0:1]
	s_andn2_b64 vcc, exec, s[2:3]
	s_cbranch_vccnz .LBB0_1164
	s_waitcnt vmcnt(0)
	s_barrier
	s_mov_b64 s[2:3], exec
	v_readlane_b32 s4, v246, 0
	v_readlane_b32 s5, v246, 1
	s_and_b64 s[4:5], s[2:3], s[4:5]
	s_mov_b64 exec, s[4:5]
	s_cbranch_execz .LBB0_1163
	s_add_i32 s4, 0, 0x23fc0
	v_mov_b32_e32 v0, s4
	s_waitcnt vmcnt(0) expcnt(0) lgkmcnt(0)
	ds_read_b32 v2, v0
	s_add_i32 s4, 0, 0x23fc4
	v_mov_b32_e32 v0, s4
	ds_read_b32 v0, v0
	s_waitcnt lgkmcnt(1)
	v_cmp_ne_u32_e32 vcc, 0, v2
	s_cbranch_vccnz .LBB0_1127
	s_load_dwordx2 s[8:9], s[96:97], 0x4
	s_add_u32 s4, s82, 0x80200
	s_addc_u32 s5, s83, 0
	s_add_u32 s6, s82, 0x80400
	s_addc_u32 s7, s83, 0
	s_waitcnt lgkmcnt(0)
	s_mul_i32 s50, s8, s89
	s_add_u32 s8, s82, 0x80500
	s_mul_i32 s50, s50, s9
	s_addc_u32 s9, s83, 0
	s_add_u32 s10, s82, 0x80600
	s_addc_u32 s11, s83, 0
	s_add_u32 s12, s82, 0x80700
	s_addc_u32 s13, s83, 0
	s_add_u32 s14, s82, 0x80800
	s_addc_u32 s15, s83, 0
	s_add_u32 s16, s82, 0x80900
	s_addc_u32 s17, s83, 0
	s_add_u32 s18, s82, 0x80a00
	s_addc_u32 s19, s83, 0
	s_add_u32 s20, s82, 0x80b00
	s_addc_u32 s21, s83, 0
	s_add_u32 s22, s82, 0x80c00
	s_addc_u32 s23, s83, 0
	s_add_u32 s24, s82, 0x80d00
	s_addc_u32 s25, s83, 0
	s_add_u32 s26, s82, 0x80e00
	s_addc_u32 s27, s83, 0
	s_add_u32 s28, s82, 0x80f00
	s_addc_u32 s29, s83, 0
	s_add_u32 s30, s82, 0x81000
	s_addc_u32 s31, s83, 0
	s_add_u32 s34, s82, 0x81100
	s_addc_u32 s35, s83, 0
	s_add_u32 s36, s82, 0x81200
	s_addc_u32 s37, s83, 0
	s_add_u32 s38, s82, 0x81300
	s_addc_u32 s39, s83, 0
	s_mov_b32 s51, 1
	v_mov_b32_e32 v16, 0
	s_branch .LBB0_1115
